# defer 34% of w_up/w_down conversion (layers 1-3) from P0 into grid-barrier waits: waves 1-7 convert one item per barrier
# speedup vs baseline: 1.0065x; 1.0065x over previous
; #define LAS __attribute__((address_space(3)))
; __device__ __forceinline__ void transpose_tensor(const float* W, const float* g, int gstep, int nl, int K, int N, bf16* WT, LAS float* scr, int gw, int NGW, int lane) {
;     const int nblk = N / 32, per = (K / 64) * nblk, total = nl * per;
;     for (int it = gw; it < total; it += NGW) { const int l = it / per, r = it - l * per;
;         transpose_item(W + (size_t)l * K * N, g ? g + (size_t)l * gstep : nullptr, K, N, WT + (size_t)l * K * N, scr, r / nblk, r % nblk, lane); }
; __global__ void __launch_bounds__(NWAVES * 64, 2) fwd(Args args) {
;     ...
;         transpose_tensor(ka->in[8], ka->in[4], 2 * DM, 2, DM, NQKV, WSB(WS_WQKVA), scr, gw, NGW, lane);
;         transpose_tensor(ka->in[13], ka->in[4] + DM, 2 * DM, 2, DM, 3 * NQKV, WSB(WS_WQKVB), scr, gw, NGW, lane);
;         transpose_tensor(ka->in[12], nullptr, 0, 2, DM, DM, WSB(WS_WOA), scr, gw, NGW, lane);
;         transpose_tensor(ka->in[17], nullptr, 0, 2, DM, DM, WSB(WS_WOB), scr, gw, NGW, lane);
;         transpose_tensor(ka->in[18], ka->in[5], DM, 4, DM, XHEAD * HD, WSB(WS_WQX), scr, gw, NGW, lane);
;         transpose_tensor(ka->in[19], nullptr, 0, 4, DM, 2 * XHEAD * HD, WSB(WS_WKVX), scr, gw, NGW, lane);
;         transpose_tensor(ka->in[22], nullptr, 0, 4, XHEAD * HD, DM, WSB(WS_WOX), scr, gw, NGW, lane);
;         transpose_tensor(ka->in[23], ka->in[7], DM, 4, DM, DFF, WSB(WS_WUP), scr, gw, NGW, lane);
;         transpose_tensor(ka->in[24], nullptr, 0, 4, DFF, DM, WSB(WS_WDN), scr, gw, NGW, lane);
.LBB0_13:
.LBB0_14:
	v_readlane_b32 s10, v252, 0
	v_readlane_b32 s11, v252, 1
	s_mov_b32 s61, 0
	v_writelane_b32 v255, s61, 6
	v_lshrrev_b32_e32 v100, 6, v0
	v_and_b32_e32 v101, 63, v0
	s_load_dwordx2 s[12:13], s[10:11], 0xd0
	v_readfirstlane_b32 s14, v100
	v_lshrrev_b32_e32 v102, 5, v101
	v_and_b32_e32 v103, 31, v101
	v_and_b32_e32 v105, 7, v101
	v_lshrrev_b32_e32 v106, 3, v101
	s_lshl_b32 s15, s59, 3
	s_add_i32 s15, s15, s14
	s_lshl_b32 s16, s60, 3
	s_lshl_b32 s17, s14, 14
	s_mul_i32 s69, s60, 56
	s_min_u32 s69, s69, 0x4000
	s_min_u32 s67, s69, 0x2000
	s_max_u32 s68, s69, 0x2000
	s_sub_u32 s68, s68, 0x2000
	v_mad_u32_u24 v104, v102, 33, v103
	v_lshl_add_u32 v104, v104, 2, s17
	v_mul_u32_u24_e32 v107, 0x108, v105
	v_add_u32_e32 v107, v107, v106
	v_lshl_add_u32 v107, v107, 2, s17
	v_lshlrev_b32_e32 v108, 5, v105
	v_lshlrev_b32_e32 v109, 2, v103
	v_lshlrev_b32_e32 v105, 4, v105
	s_mov_b32 s18, 0
	s_waitcnt lgkmcnt(0)
.Lwt_dispatch:
	s_cmp_eq_u32 s18, 0
	s_cbranch_scc1 .Lwt_p0
	s_cmp_eq_u32 s18, 1
	s_cbranch_scc1 .Lwt_p1
	s_cmp_eq_u32 s18, 2
	s_cbranch_scc1 .Lwt_p2
	s_cmp_eq_u32 s18, 3
	s_cbranch_scc1 .Lwt_p3
	s_cmp_eq_u32 s18, 4
	s_cbranch_scc1 .Lwt_p4
	s_cmp_eq_u32 s18, 5
	s_cbranch_scc1 .Lwt_p5
	s_cmp_eq_u32 s18, 6
	s_cbranch_scc1 .Lwt_p6
	s_cmp_eq_u32 s18, 7
	s_cbranch_scc1 .Lwt_p7
	s_cmp_eq_u32 s18, 8
	s_cbranch_scc1 .Lwt_p8
	s_cmp_eq_u32 s18, 9
	s_cbranch_scc1 .Lwt_p9
	s_cmp_eq_u32 s18, 10
	s_cbranch_scc1 .Lwt_p10
	s_cmp_eq_u32 s18, 11
	s_cbranch_scc1 .Lwt_p11
	s_cmp_eq_u32 s18, 12
	s_cbranch_scc1 .Lwt_p12
	s_cmp_eq_u32 s18, 13
	s_cbranch_scc1 .Lwt_p13
	s_cmp_eq_u32 s18, 14
	s_cbranch_scc1 .Lwt_p14
	s_branch .Lwt_end
.Lwt_p0:
	s_movk_i32 s19, 0x40
	s_mov_b32 s62, 0x800
	s_mov_b32 s63, 0x1800
	s_mov_b32 s26, 0xaaaab
	s_mov_b32 s28, 0x1555556
	s_mov_b32 s34, 0x1000000
	s_mov_b32 s65, 0x0
	s_mov_b32 s66, 0x3000
	s_movk_i32 s20, 0x20
	s_mov_b32 s21, 0x0
	s_mov_b32 s22, 0x4000
	s_mov_b32 s23, 1
	s_branch .Lwt_run
.Lwt_p1:
	s_movk_i32 s19, 0x68
	s_mov_b32 s62, 0x800
	s_mov_b32 s63, 0x4800
	s_mov_b32 s26, 0x38e39
	s_mov_b32 s28, 0x71c71d
	s_mov_b32 s34, 0x4000000
	s_mov_b32 s65, 0x0
	s_mov_b32 s66, 0x9000
	s_movk_i32 s20, 0x20
	s_mov_b32 s21, 0x2000
	s_mov_b32 s22, 0x4000
	s_mov_b32 s23, 1
	s_branch .Lwt_run
.Lwt_p2:
	s_movk_i32 s19, 0x60
	s_mov_b32 s62, 0x800
	s_mov_b32 s63, 0x800
	s_mov_b32 s26, 0x200000
	s_mov_b32 s28, 0x4000000
	s_mov_b32 s34, 0xd000000
	s_mov_b32 s65, 0x0
	s_mov_b32 s66, 0x1000
	s_movk_i32 s20, 0x20
	s_mov_b32 s21, 0
	s_mov_b32 s22, 0
	s_mov_b32 s23, 0
	s_branch .Lwt_run
.Lwt_p3:
	s_movk_i32 s19, 0x88
	s_mov_b32 s62, 0x800
	s_mov_b32 s63, 0x800
	s_mov_b32 s26, 0x200000
	s_mov_b32 s28, 0x4000000
	s_mov_b32 s34, 0xe000000
	s_mov_b32 s65, 0x0
	s_mov_b32 s66, 0x1000
	s_movk_i32 s20, 0x20
	s_mov_b32 s21, 0
	s_mov_b32 s22, 0
	s_mov_b32 s23, 0
	s_branch .Lwt_run
.Lwt_p4:
	s_movk_i32 s19, 0x90
	s_mov_b32 s62, 0x800
	s_mov_b32 s63, 0x200
	s_mov_b32 s26, 0x800000
	s_mov_b32 s28, 0x10000000
	s_mov_b32 s34, 0xf000000
	s_mov_b32 s65, 0x0
	s_mov_b32 s66, 0x800
	s_movk_i32 s20, 0x28
	s_mov_b32 s21, 0x0
	s_mov_b32 s22, 0x2000
	s_mov_b32 s23, 1
	s_branch .Lwt_run
.Lwt_p5:
	s_movk_i32 s19, 0x98
	s_mov_b32 s62, 0x800
	s_mov_b32 s63, 0x400
	s_mov_b32 s26, 0x400000
	s_mov_b32 s28, 0x8000000
	s_mov_b32 s34, 0xf800000
	s_mov_b32 s65, 0x0
	s_mov_b32 s66, 0x1000
	s_movk_i32 s20, 0x20
	s_mov_b32 s21, 0
	s_mov_b32 s22, 0
	s_mov_b32 s23, 0
	s_branch .Lwt_run
.Lwt_p6:
	s_movk_i32 s19, 0xb0
	s_mov_b32 s62, 0x200
	s_mov_b32 s63, 0x800
	s_mov_b32 s26, 0x800000
	s_mov_b32 s28, 0x4000000
	s_mov_b32 s34, 0x10800000
	s_mov_b32 s65, 0x0
	s_mov_b32 s66, 0x800
	s_movk_i32 s20, 0x20
	s_mov_b32 s21, 0
	s_mov_b32 s22, 0
	s_mov_b32 s23, 0
	s_branch .Lwt_run
.Lwt_p7:
	s_movk_i32 s19, 0xb8
	s_mov_b32 s62, 0x800
	s_mov_b32 s63, 0x2000
	s_mov_b32 s26, 0x80000
	s_mov_b32 s28, 0x1000000
	s_mov_b32 s34, 0x11000000
	s_mov_b32 s65, 0x0
	s_mov_b32 s66, 0x2000
	s_movk_i32 s20, 0x38
	s_mov_b32 s21, 0x0
	s_mov_b32 s22, 0x2000
	s_mov_b32 s23, 1
	s_branch .Lwt_run
.Lwt_p8:
	s_movk_i32 s19, 0xc0
	s_mov_b32 s62, 0x2000
	s_mov_b32 s63, 0x800
	s_mov_b32 s26, 0x80000
	s_mov_b32 s28, 0x4000000
	s_mov_b32 s34, 0x19000000
	s_mov_b32 s65, 0x0
	s_mov_b32 s66, 0x2000
	s_movk_i32 s20, 0x20
	s_mov_b32 s21, 0
	s_mov_b32 s22, 0
	s_mov_b32 s23, 0
	s_branch .Lwt_run
.Lwt_p9:
	s_movk_i32 s19, 0xb8
	s_mov_b32 s62, 0x800
	s_mov_b32 s63, 0x2000
	s_mov_b32 s26, 0x80000
	s_mov_b32 s28, 0x1000000
	s_mov_b32 s34, 0x11000000
	s_add_u32 s65, s67, 0x2000
	s_mov_b32 s66, 0x4000
	s_movk_i32 s20, 0x38
	s_mov_b32 s21, 0x0
	s_mov_b32 s22, 0x2000
	s_mov_b32 s23, 1
	s_branch .Lwt_run
.Lwt_p10:
	s_movk_i32 s19, 0xc0
	s_mov_b32 s62, 0x2000
	s_mov_b32 s63, 0x800
	s_mov_b32 s26, 0x80000
	s_mov_b32 s28, 0x4000000
	s_mov_b32 s34, 0x19000000
	s_add_u32 s65, s68, 0x2000
	s_mov_b32 s66, 0x4000
	s_movk_i32 s20, 0x20
	s_mov_b32 s21, 0
	s_mov_b32 s22, 0
	s_mov_b32 s23, 0
	s_branch .Lwt_run
.Lwt_p11:
	s_movk_i32 s19, 0xb8
	s_mov_b32 s62, 0x800
	s_mov_b32 s63, 0x2000
	s_mov_b32 s26, 0x80000
	s_mov_b32 s28, 0x1000000
	s_mov_b32 s34, 0x11000000
	s_add_u32 s65, s67, 0x4000
	s_mov_b32 s66, 0x6000
	s_movk_i32 s20, 0x38
	s_mov_b32 s21, 0x0
	s_mov_b32 s22, 0x2000
	s_mov_b32 s23, 1
	s_branch .Lwt_run
; #define LAS __attribute__((address_space(3)))
; __device__ __forceinline__ void transpose_item(const float* W, const float* g  , int K, int N, bf16* WT, LAS float* scr, int kb, int nb, int lane) {
;     const int k0 = 64 * kb, n0 = 32 * nb;
; #pragma unroll 8
;     for (int i = 0; i < 32; ++i) { const int kk = 2 * i + (lane >> 5); const float gv = g ? g[k0 + kk] : 1.f; scr[kk * 33 + (lane & 31)] = W[(size_t)(k0 + kk) * N + n0 + (lane & 31)] * gv; }
; __device__ __forceinline__ void transpose_tensor(const float* W, const float* g, int gstep, int nl, int K, int N, bf16* WT, LAS float* scr, int gw, int NGW, int lane) {
;     const int nblk = N / 32, per = (K / 64) * nblk, total = nl * per;
;     for (int it = gw; it < total; it += NGW) { const int l = it / per, r = it - l * per;
;         transpose_item(W + (size_t)l * K * N, g ? g + (size_t)l * gstep : nullptr, K, N, WT + (size_t)l * K * N, scr, r / nblk, r % nblk, lane); }
.Lwt_p12:
	s_movk_i32 s19, 0xc0
	s_mov_b32 s62, 0x2000
	s_mov_b32 s63, 0x800
	s_mov_b32 s26, 0x80000
	s_mov_b32 s28, 0x4000000
	s_mov_b32 s34, 0x19000000
	s_add_u32 s65, s68, 0x4000
	s_mov_b32 s66, 0x6000
	s_movk_i32 s20, 0x20
	s_mov_b32 s21, 0
	s_mov_b32 s22, 0
	s_mov_b32 s23, 0
	s_branch .Lwt_run
.Lwt_p13:
	s_movk_i32 s19, 0xb8
	s_mov_b32 s62, 0x800
	s_mov_b32 s63, 0x2000
	s_mov_b32 s26, 0x80000
	s_mov_b32 s28, 0x1000000
	s_mov_b32 s34, 0x11000000
	s_add_u32 s65, s67, 0x6000
	s_mov_b32 s66, 0x8000
	s_movk_i32 s20, 0x38
	s_mov_b32 s21, 0x0
	s_mov_b32 s22, 0x2000
	s_mov_b32 s23, 1
	s_branch .Lwt_run
.Lwt_p14:
	s_movk_i32 s19, 0xc0
	s_mov_b32 s62, 0x2000
	s_mov_b32 s63, 0x800
	s_mov_b32 s26, 0x80000
	s_mov_b32 s28, 0x4000000
	s_mov_b32 s34, 0x19000000
	s_add_u32 s65, s68, 0x6000
	s_mov_b32 s66, 0x8000
	s_movk_i32 s20, 0x20
	s_mov_b32 s21, 0
	s_mov_b32 s22, 0
	s_mov_b32 s23, 0
	s_branch .Lwt_run
.Lwt_run:
	s_load_dwordx2 s[38:39], s[10:11], s19
	s_load_dwordx2 s[40:41], s[10:11], s20
	s_lshr_b32 s27, s63, 5
	s_lshr_b32 s25, s62, 6
	s_mul_i32 s25, s25, s27
	s_mov_b32 s24, s66
	s_lshl_b32 s30, s63, 8
	s_mul_i32 s29, s62, s63
	s_lshl_b32 s31, s29, 1
	s_lshl_b32 s29, s29, 2
	s_lshl_b32 s32, s62, 6
	s_lshl_b32 s35, s63, 2
	s_lshl_b32 s36, s62, 1
	s_add_u32 s42, s12, s34
	s_addc_u32 s43, s13, 0
	v_mad_u32_u24 v110, v102, s35, v109
	s_lshl_b32 s61, s35, 1
	v_add_u32_e32 v111, s61, v110
	v_add_u32_e32 v112, s61, v111
	v_add_u32_e32 v113, s61, v112
	v_add_u32_e32 v114, s61, v113
	v_add_u32_e32 v115, s61, v114
	v_add_u32_e32 v116, s61, v115
	v_add_u32_e32 v117, s61, v116
	v_add_u32_e32 v118, s61, v117
	v_add_u32_e32 v119, s61, v118
	v_add_u32_e32 v120, s61, v119
	v_add_u32_e32 v121, s61, v120
	v_add_u32_e32 v122, s61, v121
	v_add_u32_e32 v123, s61, v122
	v_add_u32_e32 v124, s61, v123
	v_add_u32_e32 v125, s61, v124
	v_add_u32_e32 v126, s61, v125
	v_add_u32_e32 v127, s61, v126
	v_add_u32_e32 v128, s61, v127
	v_add_u32_e32 v129, s61, v128
	v_add_u32_e32 v130, s61, v129
	v_add_u32_e32 v131, s61, v130
	v_add_u32_e32 v132, s61, v131
	v_add_u32_e32 v133, s61, v132
	v_add_u32_e32 v134, s61, v133
	v_add_u32_e32 v135, s61, v134
	v_add_u32_e32 v136, s61, v135
	v_add_u32_e32 v137, s61, v136
	v_add_u32_e32 v138, s61, v137
	v_add_u32_e32 v139, s61, v138
	v_add_u32_e32 v140, s61, v139
	v_add_u32_e32 v141, s61, v140
	v_mad_u32_u24 v142, v106, s36, v105
	s_lshl_b32 s61, s36, 3
	v_add_u32_e32 v143, s61, v142
	v_add_u32_e32 v144, s61, v143
	v_add_u32_e32 v145, s61, v144
	v_mov_b32_e32 v178, 1.0
	v_mov_b32_e32 v179, 1.0
	v_mov_b32_e32 v180, 1.0
	v_mov_b32_e32 v181, 1.0
	v_mov_b32_e32 v182, 1.0
	v_mov_b32_e32 v183, 1.0
	v_mov_b32_e32 v184, 1.0
	v_mov_b32_e32 v185, 1.0
	s_add_u32 s37, s15, s65
	s_waitcnt lgkmcnt(0)
	s_add_u32 s40, s40, s21
	s_addc_u32 s41, s41, 0
	s_cmp_lt_u32 s37, s24
	s_cbranch_scc0 .Lwt_next
	s_mul_hi_u32 s54, s37, s26
	s_mul_i32 s55, s54, s25
	s_sub_u32 s55, s37, s55
	s_mul_hi_u32 s56, s55, s28
	s_mul_i32 s57, s56, s27
	s_sub_u32 s57, s55, s57
	s_mul_i32 s58, s54, s29
	s_mul_i32 s61, s56, s30
	s_add_u32 s58, s58, s61
	s_lshl_b32 s61, s57, 7
	s_add_u32 s58, s58, s61
	s_add_u32 s44, s38, s58
	s_addc_u32 s45, s39, 0
	s_mul_i32 s58, s54, s31
	s_mul_i32 s61, s57, s32
	s_add_u32 s58, s58, s61
	s_lshl_b32 s61, s56, 7
	s_add_u32 s58, s58, s61
	s_add_u32 s50, s42, s58
	s_addc_u32 s51, s43, 0
	s_mul_i32 s58, s54, s22
	s_lshl_b32 s61, s56, 8
	s_add_u32 s58, s58, s61
	s_add_u32 s48, s40, s58
	s_addc_u32 s49, s41, 0
	global_load_dword v146, v110, s[44:45] nt
	global_load_dword v147, v111, s[44:45] nt
	global_load_dword v148, v112, s[44:45] nt
	global_load_dword v149, v113, s[44:45] nt
	global_load_dword v150, v114, s[44:45] nt
	global_load_dword v151, v115, s[44:45] nt
	global_load_dword v152, v116, s[44:45] nt
	global_load_dword v153, v117, s[44:45] nt
	global_load_dword v154, v118, s[44:45] nt
	global_load_dword v155, v119, s[44:45] nt
	global_load_dword v156, v120, s[44:45] nt
	global_load_dword v157, v121, s[44:45] nt
	global_load_dword v158, v122, s[44:45] nt
	global_load_dword v159, v123, s[44:45] nt
	global_load_dword v160, v124, s[44:45] nt
	global_load_dword v161, v125, s[44:45] nt
	global_load_dword v162, v126, s[44:45] nt
	global_load_dword v163, v127, s[44:45] nt
	global_load_dword v164, v128, s[44:45] nt
	global_load_dword v165, v129, s[44:45] nt
	global_load_dword v166, v130, s[44:45] nt
	global_load_dword v167, v131, s[44:45] nt
	global_load_dword v168, v132, s[44:45] nt
	global_load_dword v169, v133, s[44:45] nt
	global_load_dword v170, v134, s[44:45] nt
	global_load_dword v171, v135, s[44:45] nt
	global_load_dword v172, v136, s[44:45] nt
	global_load_dword v173, v137, s[44:45] nt
	global_load_dword v174, v138, s[44:45] nt
	global_load_dword v175, v139, s[44:45] nt
	global_load_dword v176, v140, s[44:45] nt
	global_load_dword v177, v141, s[44:45] nt
	s_cmp_eq_u32 s23, 0
	s_cbranch_scc1 .Lwt_nog_a
	global_load_dwordx4 v[178:181], v108, s[48:49]
	global_load_dwordx4 v[182:185], v108, s[48:49] offset:16

; #define GAS __attribute__((address_space(1)))
; #define LAS __attribute__((address_space(3)))
; #define LDS_WAIT() asm volatile("s_waitcnt lgkmcnt(0)" ::: "memory")
; __device__ __forceinline__ unsigned pk2(float lo, float hi) { return f2bf(lo) | (f2bf(hi) << 16); }
; __device__ __forceinline__ void transpose_item(const float* W, const float* g  , int K, int N, bf16* WT, LAS float* scr, int kb, int nb, int lane) {
;     const int k0 = 64 * kb, n0 = 32 * nb;
; #pragma unroll 8
;     for (int i = 0; i < 32; ++i) { const int kk = 2 * i + (lane >> 5); const float gv = g ? g[k0 + kk] : 1.f; scr[kk * 33 + (lane & 31)] = W[(size_t)(k0 + kk) * N + n0 + (lane & 31)] * gv; }
;     LDS_WAIT(); asm volatile("" ::: "memory");
;     const int c = lane & 7;
; #pragma unroll
;     for (int j = 0; j < 4; ++j) { const int n = (lane >> 3) + 8 * j; const LAS float* s = scr + (8 * c) * 33 + n;
;         v4u o; o.x = pk2(s[0 * 33], s[1 * 33]); o.y = pk2(s[2 * 33], s[3 * 33]); o.z = pk2(s[4 * 33], s[5 * 33]); o.w = pk2(s[6 * 33], s[7 * 33]);
;         *(GAS v4u*)(WT + (size_t)(n0 + n) * K + k0 + 8 * c) = o; }
;     LDS_WAIT(); asm volatile("" ::: "memory");
; }
; __device__ __forceinline__ void transpose_tensor(const float* W, const float* g, int gstep, int nl, int K, int N, bf16* WT, LAS float* scr, int gw, int NGW, int lane) {
;     const int nblk = N / 32, per = (K / 64) * nblk, total = nl * per;
;     for (int it = gw; it < total; it += NGW) { const int l = it / per, r = it - l * per;
;         transpose_item(W + (size_t)l * K * N, g ? g + (size_t)l * gstep : nullptr, K, N, WT + (size_t)l * K * N, scr, r / nblk, r % nblk, lane); }
.Lwt_end:
	s_waitcnt lgkmcnt(0)
	s_branch .Lwb_over
.Lwb_entry:
	v_readlane_b32 s96, v255, 6
	v_readfirstlane_b32 s94, v0
	s_add_u32 s95, s96, 1
	s_lshr_b32 s94, s94, 6
	v_writelane_b32 v255, s95, 6
	s_cmp_eq_u32 s94, 0
	s_cbranch_scc1 .Lwb_ret
	s_mov_b32 s85, 1
	s_mov_b32 s84, s96
	s_cmp_lt_u32 s84, 8
	s_cbranch_scc1 .Lwb_go
	s_mov_b32 s85, 2
	s_sub_u32 s84, s96, 9
	s_cmp_lt_u32 s84, 8
	s_cbranch_scc1 .Lwb_go
	s_mov_b32 s85, 3
	s_sub_u32 s84, s96, 19
	s_cmp_lt_u32 s84, 8
	s_cbranch_scc1 .Lwb_go
	s_branch .Lwb_ret
.Lwb_go:
	s_mul_i32 s83, s60, 7
	s_mul_i32 s84, s84, s83
	s_mul_i32 s83, s59, 7
	s_add_u32 s84, s84, s83
	s_add_u32 s84, s84, s94
	s_sub_u32 s84, s84, 1
	s_mul_i32 s69, s60, 56
	s_min_u32 s69, s69, 0x4000
	s_cmp_lt_u32 s84, s69
	s_cbranch_scc0 .Lwb_ret
	v_readlane_b32 s92, v252, 0
	v_readlane_b32 s93, v252, 1
	s_load_dwordx2 s[90:91], s[92:93], 0xd0
	s_cmp_lt_u32 s84, 0x2000
	s_cbranch_scc0 .Lwb_dn
	s_load_dwordx2 s[88:89], s[92:93], 0xb8
	s_load_dwordx2 s[86:87], s[92:93], 0x38
	s_lshr_b32 s83, s84, 8
	s_and_b32 s82, s84, 0xff
	s_mov_b32 s73, 0x8000
	s_mov_b32 s72, 0x1000
	s_mov_b32 s78, 0x200000
	s_mov_b32 s77, 0x20000
	s_mov_b32 s75, 0x11000000
	s_mov_b32 s74, 1
	s_branch .Lwb_cm
.Lwb_dn:
	s_load_dwordx2 s[88:89], s[92:93], 0xc0
	s_sub_u32 s81, s84, 0x2000
	s_lshr_b32 s83, s81, 6
	s_and_b32 s82, s81, 63
	s_mov_b32 s73, 0x2000
	s_mov_b32 s72, 0x4000
	s_mov_b32 s78, 0x80000
	s_mov_b32 s77, 0x80000
	s_mov_b32 s75, 0x19000000
	s_mov_b32 s74, 0
.Lwb_cm:
	s_mov_b64 s[70:71], exec
	s_mov_b64 exec, -1
	v_and_b32_e32 v19, 63, v0
	v_lshrrev_b32_e32 v20, 5, v19
	v_and_b32_e32 v21, 31, v19
	v_and_b32_e32 v22, 7, v19
	v_lshrrev_b32_e32 v23, 3, v19
	s_lshl_b32 s81, s94, 14
	v_lshlrev_b32_e32 v64, 2, v21
	v_mad_u32_u24 v64, v20, s73, v64
	v_lshlrev_b32_e32 v65, 4, v22
	v_mad_u32_u24 v65, v23, s72, v65
	v_lshlrev_b32_e32 v66, 5, v22
	v_mad_u32_u24 v67, v20, 33, v21
	v_lshl_add_u32 v67, v67, 2, s81
	v_mul_u32_u24_e32 v68, 0x108, v22
	v_add_u32_e32 v68, v68, v23
	v_lshl_add_u32 v68, v68, 2, s81
	s_lshl_b32 s80, s73, 1
	s_lshl_b32 s79, s72, 3
	s_waitcnt lgkmcnt(0)
	s_lshl_b32 s81, s85, 26
	s_mul_i32 s76, s83, s78
	s_add_u32 s81, s81, s76
	s_lshl_b32 s76, s82, 7
	s_add_u32 s81, s81, s76
	s_add_u32 s88, s88, s81
	s_addc_u32 s89, s89, 0
	s_lshl_b32 s81, s85, 25
	s_add_u32 s81, s81, s75
	s_mul_i32 s76, s82, s77
	s_add_u32 s81, s81, s76
	s_lshl_b32 s76, s83, 7
	s_add_u32 s81, s81, s76
	s_add_u32 s90, s90, s81
	s_addc_u32 s91, s91, 0
	global_load_dword v24, v64, s[88:89] nt
	s_add_u32 s88, s88, s80
	s_addc_u32 s89, s89, 0
	global_load_dword v25, v64, s[88:89] nt
	s_add_u32 s88, s88, s80
	s_addc_u32 s89, s89, 0
	global_load_dword v26, v64, s[88:89] nt
	s_add_u32 s88, s88, s80
	s_addc_u32 s89, s89, 0
	global_load_dword v27, v64, s[88:89] nt
	s_add_u32 s88, s88, s80
	s_addc_u32 s89, s89, 0
	global_load_dword v28, v64, s[88:89] nt
	s_add_u32 s88, s88, s80
	s_addc_u32 s89, s89, 0
	global_load_dword v29, v64, s[88:89] nt
	s_add_u32 s88, s88, s80
	s_addc_u32 s89, s89, 0
	global_load_dword v30, v64, s[88:89] nt
	s_add_u32 s88, s88, s80
	s_addc_u32 s89, s89, 0
	global_load_dword v31, v64, s[88:89] nt
	s_add_u32 s88, s88, s80
	s_addc_u32 s89, s89, 0
	global_load_dword v32, v64, s[88:89] nt
	s_add_u32 s88, s88, s80
	s_addc_u32 s89, s89, 0
	global_load_dword v33, v64, s[88:89] nt
	s_add_u32 s88, s88, s80
	s_addc_u32 s89, s89, 0
	global_load_dword v34, v64, s[88:89] nt
	s_add_u32 s88, s88, s80
	s_addc_u32 s89, s89, 0
	global_load_dword v35, v64, s[88:89] nt
	s_add_u32 s88, s88, s80
	s_addc_u32 s89, s89, 0
	global_load_dword v36, v64, s[88:89] nt
	s_add_u32 s88, s88, s80
	s_addc_u32 s89, s89, 0
	global_load_dword v37, v64, s[88:89] nt
	s_add_u32 s88, s88, s80
	s_addc_u32 s89, s89, 0
	global_load_dword v38, v64, s[88:89] nt
	s_add_u32 s88, s88, s80
	s_addc_u32 s89, s89, 0
	global_load_dword v39, v64, s[88:89] nt
	s_add_u32 s88, s88, s80
	s_addc_u32 s89, s89, 0
	global_load_dword v40, v64, s[88:89] nt
	s_add_u32 s88, s88, s80
	s_addc_u32 s89, s89, 0
	global_load_dword v41, v64, s[88:89] nt
	s_add_u32 s88, s88, s80
	s_addc_u32 s89, s89, 0
	global_load_dword v42, v64, s[88:89] nt
	s_add_u32 s88, s88, s80
	s_addc_u32 s89, s89, 0
	global_load_dword v43, v64, s[88:89] nt
	s_add_u32 s88, s88, s80
	s_addc_u32 s89, s89, 0
	global_load_dword v44, v64, s[88:89] nt
	s_add_u32 s88, s88, s80
	s_addc_u32 s89, s89, 0
	global_load_dword v45, v64, s[88:89] nt
	s_add_u32 s88, s88, s80
	s_addc_u32 s89, s89, 0
	global_load_dword v46, v64, s[88:89] nt
	s_add_u32 s88, s88, s80
	s_addc_u32 s89, s89, 0
	global_load_dword v47, v64, s[88:89] nt
	s_add_u32 s88, s88, s80
	s_addc_u32 s89, s89, 0
	global_load_dword v48, v64, s[88:89] nt
	s_add_u32 s88, s88, s80
	s_addc_u32 s89, s89, 0
	global_load_dword v49, v64, s[88:89] nt
	s_add_u32 s88, s88, s80
	s_addc_u32 s89, s89, 0
	global_load_dword v50, v64, s[88:89] nt
	s_add_u32 s88, s88, s80
	s_addc_u32 s89, s89, 0
	global_load_dword v51, v64, s[88:89] nt
	s_add_u32 s88, s88, s80
	s_addc_u32 s89, s89, 0
	global_load_dword v52, v64, s[88:89] nt
	s_add_u32 s88, s88, s80
	s_addc_u32 s89, s89, 0
	global_load_dword v53, v64, s[88:89] nt
	s_add_u32 s88, s88, s80
	s_addc_u32 s89, s89, 0
	global_load_dword v54, v64, s[88:89] nt
	s_add_u32 s88, s88, s80
	s_addc_u32 s89, s89, 0
	global_load_dword v55, v64, s[88:89] nt
	s_cmp_eq_u32 s74, 0
	s_cbranch_scc1 .Lwb_ng
	s_lshl_b32 s81, s85, 13
	s_lshl_b32 s76, s83, 8
	s_add_u32 s81, s81, s76
	s_add_u32 s86, s86, s81
	s_addc_u32 s87, s87, 0
	global_load_dwordx4 v[56:59], v66, s[86:87]
	global_load_dwordx4 v[60:63], v66, s[86:87] offset:16
	s_branch .Lwb_ld
; #define GAS __attribute__((address_space(1)))
; #define LAS __attribute__((address_space(3)))
; #define LDS_WAIT() asm volatile("s_waitcnt lgkmcnt(0)" ::: "memory")
; __device__ __forceinline__ unsigned pk2(float lo, float hi) { return f2bf(lo) | (f2bf(hi) << 16); }
; __device__ __forceinline__ void transpose_item(const float* W, const float* g  , int K, int N, bf16* WT, LAS float* scr, int kb, int nb, int lane) {
;     ...
;     for (int i = 0; i < 32; ++i) { const int kk = 2 * i + (lane >> 5); const float gv = g ? g[k0 + kk] : 1.f; scr[kk * 33 + (lane & 31)] = W[(size_t)(k0 + kk) * N + n0 + (lane & 31)] * gv; }
;     LDS_WAIT(); asm volatile("" ::: "memory");
;     const int c = lane & 7;
; #pragma unroll
;     for (int j = 0; j < 4; ++j) { const int n = (lane >> 3) + 8 * j; const LAS float* s = scr + (8 * c) * 33 + n;
;         v4u o; o.x = pk2(s[0 * 33], s[1 * 33]); o.y = pk2(s[2 * 33], s[3 * 33]); o.z = pk2(s[4 * 33], s[5 * 33]); o.w = pk2(s[6 * 33], s[7 * 33]);
;         *(GAS v4u*)(WT + (size_t)(n0 + n) * K + k0 + 8 * c) = o; }
;     LDS_WAIT(); asm volatile("" ::: "memory");
.Lwb_ng:
	v_mov_b32_e32 v56, 1.0
	v_mov_b32_e32 v57, 1.0
	v_mov_b32_e32 v58, 1.0
	v_mov_b32_e32 v59, 1.0
	v_mov_b32_e32 v60, 1.0
	v_mov_b32_e32 v61, 1.0
	v_mov_b32_e32 v62, 1.0
	v_mov_b32_e32 v63, 1.0
.Lwb_ld:
	s_waitcnt vmcnt(0)
	ds_write_b32 v67, v24
	ds_write_b32 v67, v25 offset:264
	ds_write_b32 v67, v26 offset:528
	ds_write_b32 v67, v27 offset:792
	ds_write_b32 v67, v28 offset:1056
	ds_write_b32 v67, v29 offset:1320
	ds_write_b32 v67, v30 offset:1584
	ds_write_b32 v67, v31 offset:1848
	ds_write_b32 v67, v32 offset:2112
	ds_write_b32 v67, v33 offset:2376
	ds_write_b32 v67, v34 offset:2640
	ds_write_b32 v67, v35 offset:2904
	ds_write_b32 v67, v36 offset:3168
	ds_write_b32 v67, v37 offset:3432
	ds_write_b32 v67, v38 offset:3696
	ds_write_b32 v67, v39 offset:3960
	ds_write_b32 v67, v40 offset:4224
	ds_write_b32 v67, v41 offset:4488
	ds_write_b32 v67, v42 offset:4752
	ds_write_b32 v67, v43 offset:5016
	ds_write_b32 v67, v44 offset:5280
	ds_write_b32 v67, v45 offset:5544
	ds_write_b32 v67, v46 offset:5808
	ds_write_b32 v67, v47 offset:6072
	ds_write_b32 v67, v48 offset:6336
	ds_write_b32 v67, v49 offset:6600
	ds_write_b32 v67, v50 offset:6864
	ds_write_b32 v67, v51 offset:7128
	ds_write_b32 v67, v52 offset:7392
	ds_write_b32 v67, v53 offset:7656
	ds_write_b32 v67, v54 offset:7920
	ds_write_b32 v67, v55 offset:8184
	s_waitcnt lgkmcnt(0)
	ds_read2_b32 v[24:25], v68 offset0:0 offset1:33
	ds_read2_b32 v[26:27], v68 offset0:66 offset1:99
	ds_read2_b32 v[28:29], v68 offset0:132 offset1:165
	ds_read2_b32 v[30:31], v68 offset0:198 offset1:231
	ds_read2_b32 v[32:33], v68 offset0:8 offset1:41
	ds_read2_b32 v[34:35], v68 offset0:74 offset1:107
	ds_read2_b32 v[36:37], v68 offset0:140 offset1:173
	ds_read2_b32 v[38:39], v68 offset0:206 offset1:239
	ds_read2_b32 v[40:41], v68 offset0:16 offset1:49
	ds_read2_b32 v[42:43], v68 offset0:82 offset1:115
	ds_read2_b32 v[44:45], v68 offset0:148 offset1:181
	ds_read2_b32 v[46:47], v68 offset0:214 offset1:247
	ds_read2_b32 v[48:49], v68 offset0:24 offset1:57
	ds_read2_b32 v[50:51], v68 offset0:90 offset1:123
	ds_read2_b32 v[52:53], v68 offset0:156 offset1:189
	ds_read2_b32 v[54:55], v68 offset0:222 offset1:255
	s_waitcnt lgkmcnt(15)
	v_mul_f32_e32 v24, v56, v24
	v_mul_f32_e32 v25, v57, v25
	v_cvt_pk_bf16_f32 v24, v24, v25
	s_waitcnt lgkmcnt(14)
	v_mul_f32_e32 v26, v58, v26
	v_mul_f32_e32 v27, v59, v27
	v_cvt_pk_bf16_f32 v25, v26, v27
	s_waitcnt lgkmcnt(13)
	v_mul_f32_e32 v28, v60, v28
	v_mul_f32_e32 v29, v61, v29
	v_cvt_pk_bf16_f32 v26, v28, v29
	s_waitcnt lgkmcnt(12)
	v_mul_f32_e32 v30, v62, v30
	v_mul_f32_e32 v31, v63, v31
	v_cvt_pk_bf16_f32 v27, v30, v31
	global_store_dwordx4 v65, v[24:27], s[90:91]
	s_add_u32 s90, s90, s79
	s_addc_u32 s91, s91, 0
	s_waitcnt lgkmcnt(11)
	v_mul_f32_e32 v32, v56, v32
	v_mul_f32_e32 v33, v57, v33
	v_cvt_pk_bf16_f32 v32, v32, v33
	s_waitcnt lgkmcnt(10)
	v_mul_f32_e32 v34, v58, v34
	v_mul_f32_e32 v35, v59, v35
	v_cvt_pk_bf16_f32 v33, v34, v35
	s_waitcnt lgkmcnt(9)
	v_mul_f32_e32 v36, v60, v36
	v_mul_f32_e32 v37, v61, v37
	v_cvt_pk_bf16_f32 v34, v36, v37
	s_waitcnt lgkmcnt(8)
	v_mul_f32_e32 v38, v62, v38
	v_mul_f32_e32 v39, v63, v39
	v_cvt_pk_bf16_f32 v35, v38, v39
	global_store_dwordx4 v65, v[32:35], s[90:91]
	s_add_u32 s90, s90, s79
	s_addc_u32 s91, s91, 0
	s_waitcnt lgkmcnt(7)
	v_mul_f32_e32 v40, v56, v40
	v_mul_f32_e32 v41, v57, v41
	v_cvt_pk_bf16_f32 v40, v40, v41
	s_waitcnt lgkmcnt(6)
	v_mul_f32_e32 v42, v58, v42
	v_mul_f32_e32 v43, v59, v43
	v_cvt_pk_bf16_f32 v41, v42, v43
	s_waitcnt lgkmcnt(5)
	v_mul_f32_e32 v44, v60, v44
	v_mul_f32_e32 v45, v61, v45
	v_cvt_pk_bf16_f32 v42, v44, v45
	s_waitcnt lgkmcnt(4)
	v_mul_f32_e32 v46, v62, v46
	v_mul_f32_e32 v47, v63, v47
	v_cvt_pk_bf16_f32 v43, v46, v47
	global_store_dwordx4 v65, v[40:43], s[90:91]
	s_add_u32 s90, s90, s79
	s_addc_u32 s91, s91, 0
	s_waitcnt lgkmcnt(3)
	v_mul_f32_e32 v48, v56, v48
	v_mul_f32_e32 v49, v57, v49
	v_cvt_pk_bf16_f32 v48, v48, v49
	s_waitcnt lgkmcnt(2)
	v_mul_f32_e32 v50, v58, v50
	v_mul_f32_e32 v51, v59, v51
	v_cvt_pk_bf16_f32 v49, v50, v51
	s_waitcnt lgkmcnt(1)
	v_mul_f32_e32 v52, v60, v52
	v_mul_f32_e32 v53, v61, v53
	v_cvt_pk_bf16_f32 v50, v52, v53
	s_waitcnt lgkmcnt(0)
	v_mul_f32_e32 v54, v62, v54
	v_mul_f32_e32 v55, v63, v55
	v_cvt_pk_bf16_f32 v51, v54, v55
	global_store_dwordx4 v65, v[48:51], s[90:91]
	s_mov_b64 exec, s[70:71]
.Lwb_ret:
	s_cmp_eq_u32 s97, 0
	s_cbranch_scc1 .Lwb_ret0
	s_cmp_eq_u32 s97, 1
	s_cbranch_scc1 .Lwb_ret1
	s_cmp_eq_u32 s97, 2
	s_cbranch_scc1 .Lwb_ret2
	s_cmp_eq_u32 s97, 3
	s_cbranch_scc1 .Lwb_ret3
	s_cmp_eq_u32 s97, 4
	s_cbranch_scc1 .Lwb_ret4
	s_cmp_eq_u32 s97, 5
	s_cbranch_scc1 .Lwb_ret5
	s_cmp_eq_u32 s97, 6
	s_cbranch_scc1 .Lwb_ret6
	s_cmp_eq_u32 s97, 7
	s_cbranch_scc1 .Lwb_ret7
	s_branch .Lwb_ret0
.Lwb_over:
	v_readlane_b32 s16, v252, 0
	v_readlane_b32 s17, v252, 1
	v_mov_b32_e32 v44, v0
	s_load_dwordx2 s[6:7], s[16:17], 0xd0
	s_load_dwordx2 s[8:9], s[16:17], 0x20
	v_readfirstlane_b32 s4, v44
	s_ashr_i32 s4, s4, 6
	s_lshl_b32 s5, s59, 3
	s_lshl_b32 s13, s4, 14
	s_add_i32 s12, s4, s5
	s_lshl_b32 s14, s60, 3
	s_add_i32 s15, s13, 0
	v_lshlrev_b32_e32 v3, 3, v44
	s_waitcnt lgkmcnt(0)
	s_cmp_eq_u64 s[8:9], 0
	v_bfe_u32 v34, v44, 3, 3
	v_and_b32_e32 v3, 56, v3
	s_cselect_b64 s[18:19], -1, 0
	s_cmp_lg_u64 s[8:9], 0
	v_bfe_u32 v2, v44, 5, 1
	v_and_b32_e32 v1, 31, v44
	v_mul_u32_u24_e32 v4, 0x84, v3
	v_lshlrev_b32_e32 v6, 2, v34
	s_cselect_b64 s[10:11], -1, 0
	s_cmpk_gt_i32 s12, 0x2fff
	v_mov_b32_e32 v5, 0
	s_movk_i32 s4, 0x84
	v_add3_u32 v35, s15, v4, v6
	v_or_b32_e32 v36, 8, v34
	v_or_b32_e32 v37, 16, v34
	v_or_b32_e32 v38, 24, v34
	v_lshlrev_b32_e32 v6, 2, v1
	v_or_b32_e32 v39, 14, v2
	v_or_b32_e32 v40, 12, v2
	v_or_b32_e32 v41, 10, v2
	v_or_b32_e32 v42, 8, v2
	v_or_b32_e32 v43, 6, v2
	v_or_b32_e32 v45, 4, v2
	v_or_b32_e32 v46, 2, v2
	v_lshlrev_b32_e32 v4, 1, v3

; __device__ __forceinline__ void xcd_barrier(const XcdBarrier& b) {
;     asm volatile("s_waitcnt vmcnt(0)" ::: "memory");
;     __syncthreads();
;     if (threadIdx.x == 0) {
;         unsigned* bar = b.bar;
;         __builtin_amdgcn_s_waitcnt(0);
;         unsigned nloc = b.st[0], nx = b.st[1];
.LBB0_134:
	s_or_b64 exec, exec, s[4:5]
	v_readlane_b32 s4, v252, 4
	v_readlane_b32 s5, v252, 5
	s_cmp_lg_u32 s5, 1
	s_waitcnt lgkmcnt(0)
	s_barrier
	s_cbranch_scc0 .LBB0_189
	s_waitcnt vmcnt(0)
	s_barrier
	s_mov_b32 s97, 0
	s_branch .Lwb_entry
.Lwb_ret0:
	s_mov_b64 s[4:5], exec
	v_readlane_b32 s6, v252, 6
	v_readlane_b32 s7, v252, 7
	s_and_b64 s[6:7], s[4:5], s[6:7]
	s_mov_b64 exec, s[6:7]
	s_cbranch_execz .LBB0_188
	s_add_i32 s6, 0, 0x20160
	v_mov_b32_e32 v1, s6
	s_waitcnt vmcnt(0) expcnt(0) lgkmcnt(0)
	ds_read_b32 v3, v1
	s_add_i32 s6, 0, 0x20164
	v_mov_b32_e32 v1, s6
	ds_read_b32 v1, v1
	s_waitcnt lgkmcnt(1)
	v_cmp_ne_u32_e32 vcc, 0, v3
	s_cbranch_vccnz .LBB0_152
	v_readlane_b32 s6, v252, 2
	v_readlane_b32 s7, v252, 3
	s_load_dwordx2 s[10:11], s[6:7], 0x4
	s_add_u32 s6, s0, 0x4200
	s_addc_u32 s7, s1, 0
	s_add_u32 s8, s0, 0x4400
	s_addc_u32 s9, s1, 0
	s_waitcnt lgkmcnt(0)
	s_mul_i32 s48, s10, s60
	s_add_u32 s10, s0, 0x4500
	s_mul_i32 s48, s48, s11
	s_addc_u32 s11, s1, 0
	s_add_u32 s12, s0, 0x4600
	s_addc_u32 s13, s1, 0
	s_add_u32 s14, s0, 0x4700
	s_addc_u32 s15, s1, 0
	s_add_u32 s16, s0, 0x4800
	s_addc_u32 s17, s1, 0
	s_add_u32 s18, s0, 0x4900
	s_addc_u32 s19, s1, 0
	s_add_u32 s20, s0, 0x4a00
	s_addc_u32 s21, s1, 0
	s_add_u32 s22, s0, 0x4b00
	s_addc_u32 s23, s1, 0
	s_add_u32 s24, s0, 0x4c00
	s_addc_u32 s25, s1, 0
	s_add_u32 s26, s0, 0x4d00
	s_addc_u32 s27, s1, 0
	s_add_u32 s28, s0, 0x4e00
	s_addc_u32 s29, s1, 0
	s_add_u32 s30, s0, 0x4f00
	s_addc_u32 s31, s1, 0
	s_add_u32 s34, s0, 0x5000
	s_addc_u32 s35, s1, 0
	s_add_u32 s36, s0, 0x5100
	s_addc_u32 s37, s1, 0
	s_add_u32 s38, s0, 0x5200
	s_addc_u32 s39, s1, 0
	s_add_u32 s40, s0, 0x5300
	s_addc_u32 s41, s1, 0
	s_mov_b32 s49, 1
	v_mov_b32_e32 v17, 0
	s_branch .LBB0_140

; __device__ __forceinline__ void xcd_barrier(const XcdBarrier& b) {
;     asm volatile("s_waitcnt vmcnt(0)" ::: "memory");
;     __syncthreads();
;     if (threadIdx.x == 0) {
;         unsigned* bar = b.bar;
;         __builtin_amdgcn_s_waitcnt(0);
;         unsigned nloc = b.st[0], nx = b.st[1];
.LBB0_456:
	v_readlane_b32 s0, v254, 44
	s_add_i32 s16, s0, 1
	v_readlane_b32 s0, v252, 4
	v_readlane_b32 s1, v252, 5
	s_cmp_ge_i32 s16, s1
	s_cbranch_scc1 .LBB0_196
	s_waitcnt vmcnt(0)
	s_waitcnt vmcnt(1) lgkmcnt(0)
	s_barrier
	s_mov_b32 s97, 1
	s_branch .Lwb_entry
.Lwb_ret1:
	s_mov_b64 s[0:1], exec
	v_readlane_b32 s2, v252, 6
	v_readlane_b32 s3, v252, 7
	s_and_b64 s[2:3], s[0:1], s[2:3]
	s_mov_b64 exec, s[2:3]
	s_cbranch_execz .LBB0_195
	v_readlane_b32 s2, v254, 12
	s_waitcnt vmcnt(0) expcnt(0) lgkmcnt(0)
	s_nop 0
	v_mov_b32_e32 v2, s2
	ds_read_b32 v5, v2
	v_readlane_b32 s2, v254, 13
	s_waitcnt lgkmcnt(0)
	v_cmp_ne_u32_e32 vcc, 0, v5
	v_mov_b32_e32 v2, s2
	ds_read_b32 v4, v2
	s_cbranch_vccnz .LBB0_473
	v_readlane_b32 s4, v252, 2
	v_readlane_b32 s5, v252, 3
	s_load_dwordx2 s[2:3], s[4:5], 0x4
	s_mov_b32 s9, 1
	s_waitcnt lgkmcnt(0)
	s_mul_i32 s8, s2, s60
	s_mul_i32 s8, s8, s3
	s_branch .LBB0_461

; __device__ __forceinline__ void xcd_barrier(const XcdBarrier& b) {
;     asm volatile("s_waitcnt vmcnt(0)" ::: "memory");
;     __syncthreads();
;     if (threadIdx.x == 0) {
;         unsigned* bar = b.bar;
;         __builtin_amdgcn_s_waitcnt(0);
;         unsigned nloc = b.st[0], nx = b.st[1];
.LBB0_554:
	s_waitcnt lgkmcnt(0)
	v_readlane_b32 s0, v252, 4
	s_add_i32 s16, s20, 2
	v_readlane_b32 s1, v252, 5
	s_cmp_lt_i32 s16, s1
	s_cbranch_scc0 .LBB0_608
	s_waitcnt vmcnt(0)
	s_waitcnt vmcnt(1)
	s_barrier
	s_mov_b32 s97, 2
	s_branch .Lwb_entry

; __device__ __forceinline__ void xcd_barrier(const XcdBarrier& b) {
;     asm volatile("s_waitcnt vmcnt(0)" ::: "memory");
;     __syncthreads();
;     if (threadIdx.x == 0) {
;         unsigned* bar = b.bar;
;         __builtin_amdgcn_s_waitcnt(0);
;         unsigned nloc = b.st[0], nx = b.st[1];
.LBB0_642:
	v_readlane_b32 s0, v252, 4
	s_add_i32 s16, s20, 3
	v_readlane_b32 s1, v252, 5
	s_cmp_ge_i32 s16, s1
	s_cbranch_scc1 .LBB0_696
	s_waitcnt vmcnt(0)
	s_waitcnt vmcnt(1) lgkmcnt(0)
	s_barrier
	s_mov_b32 s97, 3
	s_branch .Lwb_entry

; __device__ __forceinline__ void xcd_barrier(const XcdBarrier& b) {
;     asm volatile("s_waitcnt vmcnt(0)" ::: "memory");
;     __syncthreads();
;     if (threadIdx.x == 0) {
;         unsigned* bar = b.bar;
;         __builtin_amdgcn_s_waitcnt(0);
;         unsigned nloc = b.st[0], nx = b.st[1];
.LBB0_709:
	v_readlane_b32 s0, v252, 4
	s_add_i32 s16, s20, 4
	v_readlane_b32 s1, v252, 5
	s_cmp_ge_i32 s16, s1
	s_barrier
	s_cbranch_scc1 .LBB0_763
	s_waitcnt vmcnt(0)
	s_barrier
	s_mov_b32 s97, 4
	s_branch .Lwb_entry

; __device__ __forceinline__ void xcd_barrier(const XcdBarrier& b) {
;     asm volatile("s_waitcnt vmcnt(0)" ::: "memory");
;     __syncthreads();
;     if (threadIdx.x == 0) {
;         unsigned* bar = b.bar;
;         __builtin_amdgcn_s_waitcnt(0);
;         unsigned nloc = b.st[0], nx = b.st[1];
.LBB0_806:
	v_readlane_b32 s0, v252, 4
	s_add_i32 s16, s20, 5
	v_readlane_b32 s1, v252, 5
	s_cmp_ge_i32 s16, s1
	s_cbranch_scc1 .LBB0_860
	s_waitcnt vmcnt(0)
	s_waitcnt vmcnt(1)
	s_barrier
	s_mov_b32 s97, 5
	s_branch .Lwb_entry

; __device__ __forceinline__ void xcd_barrier(const XcdBarrier& b) {
;     asm volatile("s_waitcnt vmcnt(0)" ::: "memory");
;     __syncthreads();
;     if (threadIdx.x == 0) {
;         unsigned* bar = b.bar;
;         __builtin_amdgcn_s_waitcnt(0);
;         unsigned nloc = b.st[0], nx = b.st[1];
.LBB0_886:
	s_waitcnt lgkmcnt(0)
	v_readlane_b32 s0, v252, 4
	s_add_i32 s16, s20, 6
	v_readlane_b32 s1, v252, 5
	s_cmp_ge_i32 s16, s1
	s_cbranch_scc1 .LBB0_940
	s_waitcnt vmcnt(0)
	s_waitcnt vmcnt(1)
	s_barrier
	s_mov_b32 s97, 6
	s_branch .Lwb_entry

; __device__ __forceinline__ void xcd_barrier(const XcdBarrier& b) {
;     asm volatile("s_waitcnt vmcnt(0)" ::: "memory");
;     __syncthreads();
;     if (threadIdx.x == 0) {
;         unsigned* bar = b.bar;
;         __builtin_amdgcn_s_waitcnt(0);
;         unsigned nloc = b.st[0], nx = b.st[1];
.LBB0_1047:
	v_readlane_b32 s0, v252, 4
	s_add_i32 s2, s20, 7
	v_readlane_b32 s1, v252, 5
	v_writelane_b32 v253, s2, 42
	s_cmp_ge_i32 s2, s1
	s_cbranch_scc1 .LBB0_192
	s_waitcnt vmcnt(0)
	s_waitcnt vmcnt(1)
	s_barrier
	s_mov_b32 s97, 7
	s_branch .Lwb_entry
